# P0: waves 4-7 run the x->bf16 conversion before the weight transposes (waves 0-3 the reverse) so the two loops overlap
# speedup vs baseline: 1.0106x; 1.0058x over previous
; __global__ void __launch_bounds__(NTHREADS, 2) hymba_fwd(Args args) {
;     ...
;         const int gw = vcu * 8 + wave, NGW = G * 8;
;         constexpr int I_IN = 16 * (NZ / 32), I_OUT = 16 * (DM / 32), I_UP = 16 * (NUP / 32), I_DN = (DFF / 64) * (DM / 32), I_MEM = 16 * (512 / 32), I_L = I_IN + I_OUT + I_UP + I_DN + I_MEM;
;         for (int it = gw; it < 2 * I_L; it += NGW) {
;             const int l = it / I_L; int r = it - l * I_L; unsigned char* wl = ws + l * WS_WL;
;             if (r < I_IN) { const int nb = r % (NZ / 32), kb = r / (NZ / 32), n0 = 32 * nb; transpose_item(ap_->in[I_WIN] + (size_t)l * DM * NZ, DM, NZ, (bf16_t*)(wl + WO_IN), kb, n0, zcol_src(ztile_logical(n0)), scr, lane, ap_->in[I_N1G] + l * DM); continue; } r -= I_IN;
.LBB0_6:
	s_or_b64 exec, exec, s[2:3]
	v_readlane_b32 s2, v254, 0
	v_readlane_b32 s3, v254, 1
	s_load_dwordx2 s[10:11], s[2:3], 0xe0
	v_readlane_b32 s5, v254, 2
	s_lshr_b32 s4, s30, 6
	s_lshl_b32 s5, s5, 3
	s_add_i32 s12, s5, s4
	s_lshl_b32 s14, s80, 3
	v_and_b32_e32 v30, 63, v31
	s_mov_b32 s99, 0
	s_cmp_lt_u32 s4, 4
	s_cbranch_scc1 P0X_te
	s_mov_b32 s99, 1
	s_branch .LBB0_69
P0X_te:
	s_cmpk_gt_i32 s12, 0x30ff
	s_cbranch_scc1 .LBB0_69
	v_lshlrev_b32_e32 v1, 3, v31
	s_lshl_b32 s4, s4, 14
	v_lshrrev_b32_e32 v9, 3, v30
	v_and_b32_e32 v10, 56, v1
	s_add_i32 s5, s4, 0
	v_lshrrev_b32_e32 v2, 5, v30
	v_mul_u32_u24_e32 v1, 0x84, v10
	v_lshlrev_b32_e32 v3, 2, v9
	v_and_b32_e32 v4, 31, v31
	v_add3_u32 v11, s5, v1, v3
	v_mul_u32_u24_e32 v3, 0x84, v2
	v_mov_b32_e32 v5, 0
	v_lshlrev_b32_e32 v6, 2, v4
	v_or_b32_e32 v3, s4, v3
	s_mov_b32 s9, 0
	v_add_u32_e32 v8, s5, v6
	s_movk_i32 s13, 0x84
	v_or_b32_e32 v38, 8, v9
	v_or_b32_e32 v39, 16, v9
	v_or_b32_e32 v40, 24, v9
	v_mov_b32_e32 v1, v2
	v_add3_u32 v41, v3, v6, 0
	v_mov_b32_e32 v7, v5
	v_or_b32_e32 v42, 14, v2
	v_lshlrev_b32_e32 v12, 2, v2
	v_mov_b32_e32 v13, v5
	v_or_b32_e32 v43, 12, v2
	v_or_b32_e32 v44, 10, v2
	v_or_b32_e32 v45, 8, v2
	v_or_b32_e32 v46, 6, v2
	v_or_b32_e32 v47, 4, v2
	v_or_b32_e32 v48, 2, v2
	s_mov_b64 s[16:17], 0x1800000
	s_mov_b64 s[18:19], 0x1200000
	s_movk_i32 s15, 0x5800
	s_mov_b64 s[20:21], 0x700000
	s_mov_b64 s[22:23], 0x500000
	s_movk_i32 s31, 0x2800
	v_lshlrev_b32_e32 v4, 2, v4
	s_mov_b32 s33, s12
	s_branch .LBB0_10

; __global__ void __launch_bounds__(NTHREADS, 2) hymba_fwd(Args args) {
;     ...
;         for (int m = gw; m < MT; m += 2 * NGW) {
;             const int m2 = m + NGW;
;             const float* xa = m < MP ? ap_->in[I_XP] + (size_t)m * DM : ap_->in[I_XS] + (size_t)(m - MP) * DM;
;             const float* xb = m2 < MP ? ap_->in[I_XP] + (size_t)m2 * DM : ap_->in[I_XS] + (size_t)((m2 < MT ? m2 : m) - MP) * DM;
;             raw_rows_to_bf16(xa, xb, XN + (size_t)m * DM, XN + (size_t)(m2 < MT ? m2 : m) * DM, PS + (size_t)m * 16, PS + (size_t)(m2 < MT ? m2 : m) * 16, lane, m2 < MT); }
.LBB0_69:
	v_lshlrev_b32_e32 v32, 3, v30
	s_cmp_eq_u32 s99, 2
	s_cbranch_scc1 .LBB0_81
	s_cmp_gt_i32 s12, 0x13fff
	s_cbranch_scc1 .LBB0_81
	v_mov_b32_e32 v33, 0
	s_waitcnt lgkmcnt(0)
	v_lshl_add_u64 v[2:3], s[10:11], 0, v[32:33]
	s_mov_b64 s[4:5], 0x4100000
	v_lshl_add_u64 v[34:35], v[2:3], 0, s[4:5]
	v_lshlrev_b32_e32 v2, 2, v30
	v_mov_b32_e32 v3, v33
	v_lshl_add_u64 v[2:3], s[10:11], 0, v[2:3]
	s_mov_b64 s[6:7], 0x3600000
	v_cmp_gt_u32_e64 s[8:9], 16, v30
	v_cmp_eq_u32_e64 s[4:5], 0, v30
	v_lshl_add_u64 v[36:37], v[2:3], 0, s[6:7]
	v_lshlrev_b32_e32 v1, 4, v30
	s_mov_b32 s16, s12
	s_branch .LBB0_72

; __global__ void __launch_bounds__(NTHREADS, 2) hymba_fwd(Args args) {
;     ...
;         for (int m = gw; m < 2 * MMEM; m += NGW) { const int l = m / MMEM, r = m - l * MMEM; const float* xr = r < NBATCH * MEMT ? ap_->in[I_MEMP] + (size_t)r * DM : ap_->in[I_MEMS] + (size_t)(r - NBATCH * MEMT) * DM;
;             rms_row_to_bf16(xr, ap_->in[I_MEMG] + l * DM, XNM + (size_t)m * DM, lane); }
.LBB0_81:
	s_cmp_eq_u32 s99, 1
	s_cbranch_scc0 P0X_cont
	s_mov_b32 s99, 2
	s_lshr_b32 s4, s30, 6
	s_branch P0X_te
P0X_cont:
	s_cmpk_gt_i32 s12, 0x1fff
	s_cbranch_scc1 .LBB0_92
	s_load_dwordx2 s[4:5], s[2:3], 0x88
	v_mov_b32_e32 v3, 0
	v_lshlrev_b32_e32 v2, 4, v30
	v_mov_b32_e32 v33, v3
	v_lshlrev_b32_e32 v1, 4, v30
	s_waitcnt lgkmcnt(0)
	s_cmp_lg_u64 s[4:5], 0
	v_lshl_add_u64 v[24:25], s[4:5], 0, v[2:3]
	s_cselect_b64 s[4:5], -1, 0
	s_ashr_i32 s13, s12, 31
	s_lshl_b64 s[6:7], s[12:13], 11
	s_add_u32 s6, s10, s6
	s_addc_u32 s7, s11, s7
	v_lshl_add_u64 v[2:3], s[6:7], 0, v[32:33]
	s_mov_b64 s[6:7], 0xe200600
	v_lshl_add_u64 v[26:27], v[2:3], 0, s[6:7]
	s_ashr_i32 s15, s14, 31
	v_cndmask_b32_e64 v2, 0, 1, s[4:5]
	s_lshl_b64 s[6:7], s[14:15], 11
	v_cmp_ne_u32_e64 s[4:5], 1, v2
	v_mov_b32_e32 v34, 0x358637bd
	s_mov_b32 s8, 0x800000
	s_branch .LBB0_84
